# v19 stack + P3 lazy-rescale softmax fast path (m=0 start, no S-m subs until first rescale)
# speedup vs baseline: 1.0174x; 1.0054x over previous
; DI void attn_a_phase(const Params& p, unsigned char* ws, unsigned char* lds, int tid) {
;     ...
;         const int hd0 = kvh * 4 + hp * 2;
;         bf16x8 qf[2][4];
; #pragma unroll
;         for (int e = 0; e < 2; ++e)
; #pragma unroll
;             for (int ks = 0; ks < 4; ++ks) qf[e][ks] = *(const bf16x8*)(q0 + (size_t)(tq0 + r) * 1024 + (hd0 + e) * 64 + ks * 16 + hh * 8);
;         f32x16 O[2][2];
;         float m[2], l[2];
; #pragma unroll
;         for (int e = 0; e < 2; ++e) {
;             m[e] = sinks[hd0 + e] * LOG2E; l[e] = hh ? 0.f : 1.f;
; #pragma unroll
;             for (int i = 0; i < 16; ++i) { O[e][0][i] = 0.f; O[e][1][i] = 0.f; }
;         }
;         const int qlo = iblk * 128 + qs * 32;
;         u32x4 rk, rv;
;     ...
;         A_LOAD(0);
;         A_STORE(0);
;         __syncthreads();
.LBB0_397:
	v_add_u32_e32 v194, s14, v210
	s_and_b32 s39, s5, 3
	v_ashrrev_i32_e32 v195, 31, v194
	v_lshl_add_u32 v217, s39, 2, v205
	v_lshlrev_b64 v[2:3], 11, v[194:195]
	v_lshl_add_u64 v[2:3], v[184:185], 0, v[2:3]
	v_lshlrev_b32_e32 v0, 7, v217
	v_lshl_add_u64 v[4:5], v[2:3], 0, v[0:1]
	v_or_b32_e32 v2, s33, v203
	v_ashrrev_i32_e32 v3, 31, v2
	s_lshl_b32 s5, s39, 6
	v_or_b32_e32 v0, s19, v203
	v_lshlrev_b64 v[2:3], 9, v[2:3]
	v_add_u32_e32 v0, s5, v0
	v_mov_b64_e32 v[6:7], s[10:11]
	flat_load_dwordx4 v[144:147], v[4:5]
	flat_load_dwordx4 v[148:151], v[4:5] offset:32
	flat_load_dwordx4 v[152:155], v[4:5] offset:64
	flat_load_dwordx4 v[156:159], v[4:5] offset:96
	flat_load_dwordx4 v[160:163], v[4:5] offset:128
	flat_load_dwordx4 v[164:167], v[4:5] offset:160
	v_lshl_add_u64 v[2:3], s[8:9], 0, v[2:3]
	s_lshl_b32 s14, s39, 7
	v_mov_b32_e32 v193, v1
	v_mad_i64_i32 v[6:7], s[42:43], v0, s22, v[6:7]
	v_lshl_add_u64 v[2:3], v[2:3], 0, s[14:15]
	v_lshl_add_u64 v[196:197], v[6:7], 0, v[192:193]
	v_lshl_add_u64 v[2:3], v[2:3], 0, v[192:193]
	v_add_co_u32_e32 v6, vcc, 0x4000, v196
	v_lshlrev_b32_e32 v0, 2, v217
	s_nop 0
	v_addc_co_u32_e32 v7, vcc, 0, v197, vcc
	global_load_dwordx4 v[176:179], v[2:3], off
	global_load_dwordx4 v[180:183], v[6:7], off
	s_nop 0
	global_load_dwordx2 v[2:3], v0, s[36:37]
	flat_load_dwordx4 v[168:171], v[4:5] offset:192
	flat_load_dwordx4 v[172:175], v[4:5] offset:224
	s_cmp_lt_i32 s34, 1
	s_waitcnt vmcnt(0)
	ds_write_b128 v207, v[176:179]
	ds_write_b128 v207, v[180:183] offset:9216
	s_waitcnt lgkmcnt(0)
	s_barrier
	s_cbranch_scc1 .LBB0_374
	v_or_b32_e32 v0, s4, v204
	v_add_u32_e32 v218, 0x9f, v0
	v_add_u32_e32 v219, 0xffffff80, v0
	v_add_u32_e32 v220, 0xffffff9f, v0
	v_add_u32_e32 v221, 0x41, v0
	v_add_u32_e32 v0, s4, v212
	s_lshl_b32 s14, s5, 1
	v_subrev_u32_e32 v222, s35, v0
	v_add_u32_e32 v0, s35, v213
	v_mov_b32_e32 v14, v1
	v_mov_b32_e32 v15, v1
	v_lshl_add_u64 v[198:199], v[186:187], 0, s[14:15]
	v_pk_mul_f32 v[200:201], v[2:3], s[38:39] op_sel_hi:[1,0]
	v_exp_f32_e32 v200, v200
	v_exp_f32_e32 v201, v201
	s_lshl_b32 s14, s18, 13
	v_subrev_u32_e32 v223, s4, v0
	v_mov_b32_e32 v0, v1
	v_mov_b32_e32 v2, v1
	v_mov_b32_e32 v3, v1
	v_mov_b32_e32 v4, v1
	v_mov_b32_e32 v5, v1
	v_mov_b32_e32 v6, v1
	v_mov_b32_e32 v7, v1
	v_mov_b32_e32 v8, v1
	v_mov_b32_e32 v9, v1
	v_mov_b32_e32 v10, v1
	v_mov_b32_e32 v11, v1
	v_mov_b32_e32 v12, v1
	v_mov_b32_e32 v13, v1
	v_mov_b64_e32 v[30:31], v[14:15]
	v_mov_b64_e32 v[46:47], v[14:15]
	v_mov_b64_e32 v[62:63], v[14:15]
	v_mov_b64_e32 v[78:79], v[14:15]
	s_addk_i32 s14, 0xff40
	s_mov_b32 s58, 0
	v_mov_b64_e32 v[28:29], v[12:13]
	v_mov_b64_e32 v[26:27], v[10:11]
	v_mov_b64_e32 v[24:25], v[8:9]
	v_mov_b64_e32 v[22:23], v[6:7]
	v_mov_b64_e32 v[20:21], v[4:5]
	v_mov_b64_e32 v[18:19], v[2:3]
	v_mov_b64_e32 v[16:17], v[0:1]
	v_mov_b64_e32 v[44:45], v[12:13]
	v_mov_b64_e32 v[42:43], v[10:11]
	v_mov_b64_e32 v[40:41], v[8:9]
	v_mov_b64_e32 v[38:39], v[6:7]
	v_mov_b64_e32 v[36:37], v[4:5]
	v_mov_b64_e32 v[34:35], v[2:3]
	v_mov_b64_e32 v[32:33], v[0:1]
	v_mov_b64_e32 v[60:61], v[12:13]
	v_mov_b64_e32 v[58:59], v[10:11]
	v_mov_b64_e32 v[56:57], v[8:9]
	v_mov_b64_e32 v[54:55], v[6:7]
	v_mov_b64_e32 v[52:53], v[4:5]
	v_mov_b64_e32 v[50:51], v[2:3]
	v_mov_b64_e32 v[48:49], v[0:1]
	v_mov_b64_e32 v[76:77], v[12:13]
	v_mov_b64_e32 v[74:75], v[10:11]
	v_mov_b64_e32 v[72:73], v[8:9]
	v_mov_b64_e32 v[70:71], v[6:7]
	v_mov_b64_e32 v[68:69], v[4:5]
	v_mov_b64_e32 v[66:67], v[2:3]
	v_mov_b64_e32 v[64:65], v[0:1]
	v_mul_f32_e32 v216, v206, v200
	v_mul_f32_e32 v193, v206, v201
	v_mov_b32_e32 v200, 0
	v_mov_b32_e32 v201, 0
	s_mov_b32 s32, 0

; DI float ex2(float v) { return __builtin_amdgcn_exp2f(v); }
; DI void softmax_pv(f32x16 (&S)[2], f32x16 (&O)[2], float& m, float& l, const unsigned char* vl, int r, int hh) {
;     float e[2][16];
;     float lt = 0.f;
; #pragma unroll
;     for (int sb = 0; sb < 2; ++sb)
; #pragma unroll
;         for (int i = 0; i < 16; ++i) { e[sb][i] = ex2(S[sb][i] - m); lt += e[sb][i]; }
;     if (__any(!(lt <= 1.0995116e12f))) {
.LBB0_416:
	s_cmp_eq_u32 s32, 0
	s_cbranch_scc1 .Lp3f_416
	v_sub_f32_e32 v2, v128, v200
	v_exp_f32_e32 v2, v2
	v_sub_f32_e32 v3, v129, v200
	v_exp_f32_e32 v3, v3
	v_sub_f32_e32 v4, v130, v200
	v_exp_f32_e32 v4, v4
	v_sub_f32_e32 v5, v131, v200
	v_exp_f32_e32 v5, v5
	v_sub_f32_e32 v7, v132, v200
	v_add_f32_e32 v6, 0, v2
	v_exp_f32_e32 v10, v7
	v_sub_f32_e32 v7, v133, v200
	v_add_f32_e32 v6, v3, v6
	v_exp_f32_e32 v11, v7
	v_sub_f32_e32 v7, v134, v200
	v_add_f32_e32 v6, v4, v6
	v_exp_f32_e32 v12, v7
	v_sub_f32_e32 v7, v135, v200
	v_add_f32_e32 v6, v5, v6
	v_exp_f32_e32 v13, v7
	v_sub_f32_e32 v7, v136, v200
	v_add_f32_e32 v6, v10, v6
	v_exp_f32_e32 v15, v7
	v_sub_f32_e32 v7, v137, v200
	v_add_f32_e32 v6, v11, v6
	v_exp_f32_e32 v224, v7
	v_sub_f32_e32 v7, v138, v200
	v_add_f32_e32 v6, v12, v6
	v_exp_f32_e32 v225, v7
	v_sub_f32_e32 v7, v139, v200
	v_add_f32_e32 v6, v13, v6
	v_exp_f32_e32 v226, v7
	v_sub_f32_e32 v7, v140, v200
	v_add_f32_e32 v6, v15, v6
	v_exp_f32_e32 v227, v7
	v_sub_f32_e32 v7, v141, v200
	v_add_f32_e32 v6, v224, v6
	v_exp_f32_e32 v228, v7
	v_sub_f32_e32 v7, v142, v200
	v_add_f32_e32 v6, v225, v6
	v_exp_f32_e32 v229, v7
	v_sub_f32_e32 v7, v143, v200
	v_add_f32_e32 v6, v226, v6
	v_exp_f32_e32 v230, v7
	v_sub_f32_e32 v7, v112, v200
	v_add_f32_e32 v6, v227, v6
	v_exp_f32_e32 v231, v7
	v_sub_f32_e32 v7, v113, v200
	v_add_f32_e32 v6, v228, v6
	v_exp_f32_e32 v232, v7
	v_sub_f32_e32 v7, v114, v200
	v_add_f32_e32 v6, v229, v6
	v_exp_f32_e32 v233, v7
	v_sub_f32_e32 v7, v115, v200
	v_add_f32_e32 v6, v230, v6
	v_exp_f32_e32 v234, v7
	v_sub_f32_e32 v7, v116, v200
	v_add_f32_e32 v6, v231, v6
	v_exp_f32_e32 v235, v7
	v_sub_f32_e32 v7, v117, v200
	v_add_f32_e32 v6, v232, v6
	v_exp_f32_e32 v236, v7
	v_sub_f32_e32 v7, v118, v200
	v_add_f32_e32 v6, v233, v6
	v_exp_f32_e32 v237, v7
	v_sub_f32_e32 v7, v119, v200
	v_add_f32_e32 v6, v234, v6
	v_exp_f32_e32 v238, v7
	v_sub_f32_e32 v7, v120, v200
	v_add_f32_e32 v6, v235, v6
	v_exp_f32_e32 v239, v7
	v_sub_f32_e32 v7, v121, v200
	v_add_f32_e32 v6, v236, v6
	v_exp_f32_e32 v240, v7
	v_sub_f32_e32 v7, v122, v200
	v_add_f32_e32 v6, v237, v6
	v_exp_f32_e32 v241, v7
	v_sub_f32_e32 v7, v123, v200
	v_add_f32_e32 v6, v238, v6
	v_exp_f32_e32 v242, v7
	v_sub_f32_e32 v7, v124, v200
	v_add_f32_e32 v6, v239, v6
	v_exp_f32_e32 v243, v7
	v_sub_f32_e32 v7, v125, v200
	v_add_f32_e32 v6, v240, v6
	v_exp_f32_e32 v244, v7
	v_sub_f32_e32 v7, v126, v200
	v_add_f32_e32 v6, v241, v6
	v_exp_f32_e32 v245, v7
	v_sub_f32_e32 v7, v127, v200
	v_add_f32_e32 v6, v242, v6
	v_exp_f32_e32 v246, v7
	v_add_f32_e32 v6, v243, v6
	v_add_f32_e32 v6, v244, v6
	v_add_f32_e32 v6, v245, v6
	v_add_f32_e32 v14, v246, v6
	v_cmp_nge_f32_e32 vcc, s24, v14
	s_cbranch_vccz .LBB0_418
; DI float ex2(float v) { return __builtin_amdgcn_exp2f(v); }
; DI float max3f_(float a, float b, float c) { return fmaxf(fmaxf(a, b), c); }
; DI void softmax_pv(f32x16 (&S)[2], f32x16 (&O)[2], float& m, float& l, const unsigned char* vl, int r, int hh) {
;     ...
;     if (__any(!(lt <= 1.0995116e12f))) {
;         float mx = max3f_(S[0][0], S[0][1], S[0][2]);
; #pragma unroll
;         for (int i = 3; i < 15; i += 2) mx = max3f_(mx, S[0][i], S[0][i + 1]);
;         mx = max3f_(mx, S[0][15], S[1][0]);
; #pragma unroll
;         for (int i = 1; i < 15; i += 2) mx = max3f_(mx, S[1][i], S[1][i + 1]);
;         mx = fmaxf(mx, S[1][15]);
;         mx = fmaxf(mx, __shfl_xor(mx, 32));
;         const float mn = fmaxf(m, mx), alpha = ex2(m - mn);
;         m = mn; l *= alpha; lt = 0.f;
; #pragma unroll
;         for (int i = 0; i < 16; ++i) { O[0][i] *= alpha; O[1][i] *= alpha; }
; #pragma unroll
;         for (int sb = 0; sb < 2; ++sb)
; #pragma unroll
;             for (int i = 0; i < 16; ++i) { e[sb][i] = ex2(S[sb][i] - mn); lt += e[sb][i]; }
;     }
.Lp3_rare0:
	s_mov_b32 s32, 1
	v_max_f32_e32 v2, v129, v129
	v_max_f32_e32 v3, v128, v128
	v_max_f32_e32 v2, v3, v2
	v_max3_f32 v2, v2, v130, v131
	v_max3_f32 v2, v2, v132, v133
	v_max3_f32 v2, v2, v134, v135
	v_max3_f32 v2, v2, v136, v137
	v_max3_f32 v2, v2, v138, v139
	v_max3_f32 v2, v2, v140, v141
	v_max3_f32 v2, v2, v142, v143
	v_max3_f32 v2, v2, v112, v113
	v_max3_f32 v2, v2, v114, v115
	v_max3_f32 v2, v2, v116, v117
	v_max3_f32 v2, v2, v118, v119
	v_and_b32_e32 v4, 64, v215
	v_max3_f32 v2, v2, v120, v121
	v_xor_b32_e32 v3, 32, v215
	v_add_u32_e32 v4, 64, v4
	v_max3_f32 v2, v2, v122, v123
	v_cmp_lt_i32_e32 vcc, v3, v4
	v_max3_f32 v2, v2, v124, v125
	v_max3_f32 v2, v2, v126, v127
	v_cndmask_b32_e32 v3, v215, v3, vcc
	v_lshlrev_b32_e32 v3, 2, v3
	ds_bpermute_b32 v3, v3, v2
	s_waitcnt lgkmcnt(0)
	v_max3_f32 v6, v200, v2, v3
	v_sub_f32_e32 v2, v200, v6
	v_exp_f32_e32 v2, v2
	v_sub_f32_e32 v4, v130, v6
	v_exp_f32_e32 v4, v4
	v_sub_f32_e32 v5, v131, v6
	v_mul_f32_e32 v216, v216, v2
	v_pk_mul_f32 v[78:79], v[78:79], v[2:3] op_sel_hi:[1,0]
	v_pk_mul_f32 v[76:77], v[76:77], v[2:3] op_sel_hi:[1,0]
	v_pk_mul_f32 v[74:75], v[74:75], v[2:3] op_sel_hi:[1,0]
	v_pk_mul_f32 v[72:73], v[72:73], v[2:3] op_sel_hi:[1,0]
	v_pk_mul_f32 v[70:71], v[70:71], v[2:3] op_sel_hi:[1,0]
	v_pk_mul_f32 v[68:69], v[68:69], v[2:3] op_sel_hi:[1,0]
	v_pk_mul_f32 v[66:67], v[66:67], v[2:3] op_sel_hi:[1,0]
	v_pk_mul_f32 v[64:65], v[64:65], v[2:3] op_sel_hi:[1,0]
	v_pk_mul_f32 v[62:63], v[62:63], v[2:3] op_sel_hi:[1,0]
	v_pk_mul_f32 v[60:61], v[60:61], v[2:3] op_sel_hi:[1,0]
	v_pk_mul_f32 v[58:59], v[58:59], v[2:3] op_sel_hi:[1,0]
	v_pk_mul_f32 v[56:57], v[56:57], v[2:3] op_sel_hi:[1,0]
	v_pk_mul_f32 v[54:55], v[54:55], v[2:3] op_sel_hi:[1,0]
	v_pk_mul_f32 v[52:53], v[52:53], v[2:3] op_sel_hi:[1,0]
	v_pk_mul_f32 v[50:51], v[50:51], v[2:3] op_sel_hi:[1,0]
	v_pk_mul_f32 v[48:49], v[48:49], v[2:3] op_sel_hi:[1,0]
	v_sub_f32_e32 v2, v128, v6
	v_exp_f32_e32 v2, v2
	v_sub_f32_e32 v3, v129, v6
	v_exp_f32_e32 v3, v3
	v_exp_f32_e32 v5, v5
	v_sub_f32_e32 v8, v132, v6
	v_add_f32_e32 v7, 0, v2
	v_exp_f32_e32 v10, v8
	v_sub_f32_e32 v8, v133, v6
	v_add_f32_e32 v7, v3, v7
	v_exp_f32_e32 v11, v8
	v_sub_f32_e32 v8, v134, v6
	v_add_f32_e32 v7, v4, v7
	v_exp_f32_e32 v12, v8
	v_sub_f32_e32 v8, v135, v6
	v_add_f32_e32 v7, v5, v7
	v_exp_f32_e32 v13, v8
	v_sub_f32_e32 v8, v136, v6
	v_add_f32_e32 v7, v10, v7
	v_exp_f32_e32 v15, v8
	v_sub_f32_e32 v8, v137, v6
	v_add_f32_e32 v7, v11, v7
	v_exp_f32_e32 v224, v8
	v_sub_f32_e32 v8, v138, v6
	v_add_f32_e32 v7, v12, v7
	v_exp_f32_e32 v225, v8
	v_sub_f32_e32 v8, v139, v6
	v_add_f32_e32 v7, v13, v7
	v_exp_f32_e32 v226, v8
	v_sub_f32_e32 v8, v140, v6
	v_add_f32_e32 v7, v15, v7
	v_exp_f32_e32 v227, v8
	v_sub_f32_e32 v8, v141, v6
	v_add_f32_e32 v7, v224, v7
	v_exp_f32_e32 v228, v8
	v_sub_f32_e32 v8, v142, v6
	v_add_f32_e32 v7, v225, v7
	v_exp_f32_e32 v229, v8
	v_sub_f32_e32 v8, v143, v6
	v_add_f32_e32 v7, v226, v7
	v_exp_f32_e32 v230, v8
	v_sub_f32_e32 v8, v112, v6
	v_add_f32_e32 v7, v227, v7
	v_exp_f32_e32 v231, v8
	v_sub_f32_e32 v8, v113, v6
	v_add_f32_e32 v7, v228, v7
	v_exp_f32_e32 v232, v8
	v_sub_f32_e32 v8, v114, v6
	v_add_f32_e32 v7, v229, v7
	v_exp_f32_e32 v233, v8
	v_sub_f32_e32 v8, v115, v6
	v_add_f32_e32 v7, v230, v7
	v_exp_f32_e32 v234, v8
	v_sub_f32_e32 v8, v116, v6
	v_add_f32_e32 v7, v231, v7
	v_exp_f32_e32 v235, v8
	v_sub_f32_e32 v8, v117, v6
	v_add_f32_e32 v7, v232, v7
	v_exp_f32_e32 v236, v8
	v_sub_f32_e32 v8, v118, v6
	v_add_f32_e32 v7, v233, v7
	v_exp_f32_e32 v237, v8
	v_sub_f32_e32 v8, v119, v6
	v_add_f32_e32 v7, v234, v7
	v_exp_f32_e32 v238, v8
	v_sub_f32_e32 v8, v120, v6
	v_add_f32_e32 v7, v235, v7
	v_exp_f32_e32 v239, v8
	v_sub_f32_e32 v8, v121, v6
	v_add_f32_e32 v7, v236, v7
	v_exp_f32_e32 v240, v8
	v_sub_f32_e32 v8, v122, v6
	v_add_f32_e32 v7, v237, v7
	v_exp_f32_e32 v241, v8
	v_sub_f32_e32 v8, v123, v6
	v_add_f32_e32 v7, v238, v7
	v_exp_f32_e32 v242, v8
	v_sub_f32_e32 v8, v124, v6
	v_add_f32_e32 v7, v239, v7
	v_exp_f32_e32 v243, v8
	v_sub_f32_e32 v8, v125, v6
	v_add_f32_e32 v7, v240, v7
	v_exp_f32_e32 v244, v8
	v_sub_f32_e32 v8, v126, v6
	v_add_f32_e32 v7, v241, v7
	v_exp_f32_e32 v245, v8
	v_sub_f32_e32 v8, v127, v6
	v_add_f32_e32 v7, v242, v7
	v_exp_f32_e32 v246, v8
	v_add_f32_e32 v7, v243, v7
	v_add_f32_e32 v7, v244, v7
	v_add_f32_e32 v7, v245, v7
	v_add_f32_e32 v14, v246, v7
	v_mov_b32_e32 v200, v6

; DI float ex2(float v) { return __builtin_amdgcn_exp2f(v); }
; DI float max3f_(float a, float b, float c) { return fmaxf(fmaxf(a, b), c); }
; DI void softmax_pv(f32x16 (&S)[2], f32x16 (&O)[2], float& m, float& l, const unsigned char* vl, int r, int hh) {
;     ...
;     if (__any(!(lt <= 1.0995116e12f))) {
;         float mx = max3f_(S[0][0], S[0][1], S[0][2]);
; #pragma unroll
;         for (int i = 3; i < 15; i += 2) mx = max3f_(mx, S[0][i], S[0][i + 1]);
;         mx = max3f_(mx, S[0][15], S[1][0]);
; #pragma unroll
;         for (int i = 1; i < 15; i += 2) mx = max3f_(mx, S[1][i], S[1][i + 1]);
;         mx = fmaxf(mx, S[1][15]);
;         mx = fmaxf(mx, __shfl_xor(mx, 32));
;         const float mn = fmaxf(m, mx), alpha = ex2(m - mn);
;         m = mn; l *= alpha; lt = 0.f;
; #pragma unroll
;         for (int i = 0; i < 16; ++i) { O[0][i] *= alpha; O[1][i] *= alpha; }
; #pragma unroll
;         for (int sb = 0; sb < 2; ++sb)
; #pragma unroll
;             for (int i = 0; i < 16; ++i) { e[sb][i] = ex2(S[sb][i] - mn); lt += e[sb][i]; }
;     }
.Lp3_rare1:
	s_mov_b32 s32, 1
	v_max_f32_e32 v0, v97, v97
	v_max_f32_e32 v15, v96, v96
	v_max_f32_e32 v0, v15, v0
	v_max3_f32 v0, v0, v98, v99
	v_max3_f32 v0, v0, v100, v101
	v_max3_f32 v0, v0, v102, v103
	v_max3_f32 v0, v0, v104, v105
	v_max3_f32 v0, v0, v106, v107
	v_max3_f32 v0, v0, v108, v109
	v_max3_f32 v0, v0, v110, v111
	v_max3_f32 v0, v0, v80, v81
	v_max3_f32 v0, v0, v82, v83
	v_max3_f32 v0, v0, v84, v85
	v_max3_f32 v0, v0, v86, v87
	v_and_b32_e32 v132, 64, v215
	v_max3_f32 v0, v0, v88, v89
	v_xor_b32_e32 v15, 32, v215
	v_add_u32_e32 v132, 64, v132
	v_max3_f32 v0, v0, v90, v91
	v_cmp_lt_i32_e32 vcc, v15, v132
	v_max3_f32 v0, v0, v92, v93
	v_max3_f32 v0, v0, v94, v95
	v_cndmask_b32_e32 v15, v215, v15, vcc
	v_lshlrev_b32_e32 v15, 2, v15
	ds_bpermute_b32 v15, v15, v0
	s_waitcnt lgkmcnt(0)
	v_max3_f32 v243, v201, v0, v15
	v_sub_f32_e32 v0, v201, v243
	v_exp_f32_e32 v0, v0
	v_sub_f32_e32 v15, v97, v243
	v_exp_f32_e32 v15, v15
	v_sub_f32_e32 v97, v100, v243
	v_mul_f32_e32 v193, v193, v0
	v_pk_mul_f32 v[46:47], v[46:47], v[0:1] op_sel_hi:[1,0]
	v_pk_mul_f32 v[44:45], v[44:45], v[0:1] op_sel_hi:[1,0]
	v_pk_mul_f32 v[42:43], v[42:43], v[0:1] op_sel_hi:[1,0]
	v_pk_mul_f32 v[40:41], v[40:41], v[0:1] op_sel_hi:[1,0]
	v_pk_mul_f32 v[38:39], v[38:39], v[0:1] op_sel_hi:[1,0]
	v_pk_mul_f32 v[36:37], v[36:37], v[0:1] op_sel_hi:[1,0]
	v_pk_mul_f32 v[34:35], v[34:35], v[0:1] op_sel_hi:[1,0]
	v_pk_mul_f32 v[32:33], v[32:33], v[0:1] op_sel_hi:[1,0]
	v_pk_mul_f32 v[30:31], v[30:31], v[0:1] op_sel_hi:[1,0]
	v_pk_mul_f32 v[28:29], v[28:29], v[0:1] op_sel_hi:[1,0]
	v_pk_mul_f32 v[26:27], v[26:27], v[0:1] op_sel_hi:[1,0]
	v_pk_mul_f32 v[24:25], v[24:25], v[0:1] op_sel_hi:[1,0]
	v_pk_mul_f32 v[22:23], v[22:23], v[0:1] op_sel_hi:[1,0]
	v_pk_mul_f32 v[20:21], v[20:21], v[0:1] op_sel_hi:[1,0]
	v_pk_mul_f32 v[18:19], v[18:19], v[0:1] op_sel_hi:[1,0]
	v_pk_mul_f32 v[16:17], v[16:17], v[0:1] op_sel_hi:[1,0]
	v_sub_f32_e32 v0, v96, v243
	v_exp_f32_e32 v0, v0
	v_sub_f32_e32 v96, v98, v243
	v_exp_f32_e32 v132, v96
	v_sub_f32_e32 v96, v99, v243
	v_exp_f32_e32 v133, v96
	v_add_f32_e32 v96, 0, v0
	v_exp_f32_e32 v134, v97
	v_sub_f32_e32 v97, v101, v243
	v_add_f32_e32 v96, v15, v96
	v_exp_f32_e32 v135, v97
	v_sub_f32_e32 v97, v102, v243
	v_add_f32_e32 v96, v132, v96
	v_exp_f32_e32 v136, v97
	v_sub_f32_e32 v97, v103, v243
	v_add_f32_e32 v96, v133, v96
	v_exp_f32_e32 v137, v97
	v_sub_f32_e32 v97, v104, v243
	v_add_f32_e32 v96, v134, v96
	v_exp_f32_e32 v138, v97
	v_sub_f32_e32 v97, v105, v243
	v_add_f32_e32 v96, v135, v96
	v_exp_f32_e32 v139, v97
	v_sub_f32_e32 v97, v106, v243
	v_add_f32_e32 v96, v136, v96
	v_exp_f32_e32 v140, v97
	v_sub_f32_e32 v97, v107, v243
	v_add_f32_e32 v96, v137, v96
	v_exp_f32_e32 v141, v97
	v_sub_f32_e32 v97, v108, v243
	v_add_f32_e32 v96, v138, v96
	v_exp_f32_e32 v142, v97
	v_sub_f32_e32 v97, v109, v243
	v_add_f32_e32 v96, v139, v96
	v_exp_f32_e32 v143, v97
	v_sub_f32_e32 v97, v110, v243
	v_add_f32_e32 v96, v140, v96
	v_exp_f32_e32 v224, v97
	v_sub_f32_e32 v97, v111, v243
	v_add_f32_e32 v96, v141, v96
	v_exp_f32_e32 v225, v97
	v_sub_f32_e32 v80, v80, v243
	v_add_f32_e32 v96, v142, v96
	v_exp_f32_e32 v226, v80
	v_sub_f32_e32 v80, v81, v243
	v_add_f32_e32 v96, v143, v96
	v_exp_f32_e32 v227, v80
	v_sub_f32_e32 v80, v82, v243
	v_add_f32_e32 v96, v224, v96
	v_exp_f32_e32 v228, v80
	v_sub_f32_e32 v80, v83, v243
	v_add_f32_e32 v96, v225, v96
	v_exp_f32_e32 v229, v80
	v_sub_f32_e32 v81, v84, v243
	v_add_f32_e32 v80, v226, v96
	v_exp_f32_e32 v230, v81
	v_sub_f32_e32 v81, v85, v243
	v_add_f32_e32 v80, v227, v80
	v_exp_f32_e32 v231, v81
	v_sub_f32_e32 v81, v86, v243
	v_add_f32_e32 v80, v228, v80
	v_exp_f32_e32 v232, v81
	v_sub_f32_e32 v81, v87, v243
	v_add_f32_e32 v80, v229, v80
	v_exp_f32_e32 v233, v81
	v_sub_f32_e32 v81, v88, v243
	v_add_f32_e32 v80, v230, v80
	v_exp_f32_e32 v234, v81
	v_sub_f32_e32 v81, v89, v243
	v_add_f32_e32 v80, v231, v80
	v_exp_f32_e32 v235, v81
	v_sub_f32_e32 v81, v90, v243
	v_add_f32_e32 v80, v232, v80
	v_exp_f32_e32 v236, v81
	v_sub_f32_e32 v81, v91, v243
	v_add_f32_e32 v80, v233, v80
	v_exp_f32_e32 v237, v81
	v_sub_f32_e32 v81, v92, v243
	v_add_f32_e32 v80, v234, v80
	v_exp_f32_e32 v238, v81
	v_sub_f32_e32 v81, v93, v243
	v_add_f32_e32 v80, v235, v80
	v_exp_f32_e32 v239, v81
	v_sub_f32_e32 v81, v94, v243
	v_add_f32_e32 v80, v236, v80
	v_exp_f32_e32 v240, v81
	v_sub_f32_e32 v81, v95, v243
	v_add_f32_e32 v80, v237, v80
	v_exp_f32_e32 v241, v81
	v_add_f32_e32 v80, v238, v80
	v_add_f32_e32 v80, v239, v80
	v_add_f32_e32 v80, v240, v80
	v_add_f32_e32 v242, v241, v80
	v_mov_b32_e32 v201, v243

; #define MFMA(a, b, c) __builtin_amdgcn_mfma_f32_32x32x16_bf16((a), (b), (c), 0, 0, 0)
; DI unsigned pk2(float a, float b) { f32x2 v = {a, b}; bf16x2_t r = __builtin_convertvector(v, bf16x2_t); return __builtin_bit_cast(unsigned, r); }
; DI float ex2(float v) { return __builtin_amdgcn_exp2f(v); }
; DI float max3f_(float a, float b, float c) { return fmaxf(fmaxf(a, b), c); }
; DI void softmax_pv(f32x16 (&S)[2], f32x16 (&O)[2], float& m, float& l, const unsigned char* vl, int r, int hh) {
;     float e[2][16];
;     float lt = 0.f;
; #pragma unroll
;     for (int sb = 0; sb < 2; ++sb)
; #pragma unroll
;         for (int i = 0; i < 16; ++i) { e[sb][i] = ex2(S[sb][i] - m); lt += e[sb][i]; }
;     if (__any(!(lt <= 1.0995116e12f))) {
;         float mx = max3f_(S[0][0], S[0][1], S[0][2]);
; #pragma unroll
;         for (int i = 3; i < 15; i += 2) mx = max3f_(mx, S[0][i], S[0][i + 1]);
;         mx = max3f_(mx, S[0][15], S[1][0]);
; #pragma unroll
;         for (int i = 1; i < 15; i += 2) mx = max3f_(mx, S[1][i], S[1][i + 1]);
;         mx = fmaxf(mx, S[1][15]);
;         mx = fmaxf(mx, __shfl_xor(mx, 32));
;         const float mn = fmaxf(m, mx), alpha = ex2(m - mn);
;         m = mn; l *= alpha; lt = 0.f;
; #pragma unroll
;         for (int i = 0; i < 16; ++i) { O[0][i] *= alpha; O[1][i] *= alpha; }
; #pragma unroll
;         for (int sb = 0; sb < 2; ++sb)
; #pragma unroll
;             for (int i = 0; i < 16; ++i) { e[sb][i] = ex2(S[sb][i] - mn); lt += e[sb][i]; }
;     }
;     l += lt;
; #pragma unroll
;     for (int sb = 0; sb < 2; ++sb)
; #pragma unroll
;         for (int s = 0; s < 2; ++s) {
;             u32x4 pw;
;             pw.x = pk2(e[sb][8 * s + 0], e[sb][8 * s + 1]); pw.y = pk2(e[sb][8 * s + 2], e[sb][8 * s + 3]);
;             pw.z = pk2(e[sb][8 * s + 4], e[sb][8 * s + 5]); pw.w = pk2(e[sb][8 * s + 6], e[sb][8 * s + 7]);
;             const bf16x8 pf = __builtin_bit_cast(bf16x8, pw);
; #pragma unroll
;             for (int db = 0; db < 2; ++db) {
;                 const bf16x8 vf = *(const bf16x8*)(vl + (db * 32 + r) * 144 + (sb * 32 + s * 16 + hh * 8) * 2);
;                 O[db] = MFMA(vf, pf, O[db]);
;             }
.Lp3f_416:
	v_exp_f32_e32 v2, v128
	v_exp_f32_e32 v3, v129
	v_exp_f32_e32 v4, v130
	v_exp_f32_e32 v5, v131
	v_add_f32_e32 v6, 0, v2
	v_exp_f32_e32 v10, v132
	v_add_f32_e32 v6, v3, v6
	v_exp_f32_e32 v11, v133
	v_add_f32_e32 v6, v4, v6
	v_exp_f32_e32 v12, v134
	v_add_f32_e32 v6, v5, v6
	v_exp_f32_e32 v13, v135
	v_add_f32_e32 v6, v10, v6
	v_exp_f32_e32 v15, v136
	v_add_f32_e32 v6, v11, v6
	v_exp_f32_e32 v224, v137
	v_add_f32_e32 v6, v12, v6
	v_exp_f32_e32 v225, v138
	v_add_f32_e32 v6, v13, v6
	v_exp_f32_e32 v226, v139
	v_add_f32_e32 v6, v15, v6
	v_exp_f32_e32 v227, v140
	v_add_f32_e32 v6, v224, v6
	v_exp_f32_e32 v228, v141
	v_add_f32_e32 v6, v225, v6
	v_exp_f32_e32 v229, v142
	v_add_f32_e32 v6, v226, v6
	v_exp_f32_e32 v230, v143
	v_add_f32_e32 v6, v227, v6
	v_exp_f32_e32 v231, v112
	v_add_f32_e32 v6, v228, v6
	v_exp_f32_e32 v232, v113
	v_add_f32_e32 v6, v229, v6
	v_exp_f32_e32 v233, v114
	v_add_f32_e32 v6, v230, v6
	v_exp_f32_e32 v234, v115
	v_add_f32_e32 v6, v231, v6
	v_exp_f32_e32 v235, v116
	v_add_f32_e32 v6, v232, v6
	v_exp_f32_e32 v236, v117
	v_add_f32_e32 v6, v233, v6
	v_exp_f32_e32 v237, v118
	v_add_f32_e32 v6, v234, v6
	v_exp_f32_e32 v238, v119
	v_add_f32_e32 v6, v235, v6
	v_exp_f32_e32 v239, v120
	v_add_f32_e32 v6, v236, v6
	v_exp_f32_e32 v240, v121
	v_add_f32_e32 v6, v237, v6
	v_exp_f32_e32 v241, v122
	v_add_f32_e32 v6, v238, v6
	v_exp_f32_e32 v242, v123
	v_add_f32_e32 v6, v239, v6
	v_exp_f32_e32 v243, v124
	v_add_f32_e32 v6, v240, v6
	v_exp_f32_e32 v244, v125
	v_add_f32_e32 v6, v241, v6
	v_exp_f32_e32 v245, v126
	v_add_f32_e32 v6, v242, v6
	v_exp_f32_e32 v246, v127
	v_add_f32_e32 v6, v243, v6
	v_add_f32_e32 v6, v244, v6
	v_add_f32_e32 v6, v245, v6
	v_add_f32_e32 v14, v246, v6
	v_cmp_nge_f32_e32 vcc, s24, v14
	s_cbranch_vccz .Lp3f_418
	s_branch .Lp3_rare0
.Lp3f_418:
	v_add_u32_e32 v120, v0, v208
	ds_read_b128 v[6:9], v120 offset:9216
	v_cvt_pk_bf16_f32 v118, v10, v11
	v_cvt_pk_bf16_f32 v119, v12, v13
	ds_read_b128 v[10:13], v120 offset:13824
	ds_read_b128 v[112:115], v120 offset:13856
	v_cvt_pk_bf16_f32 v116, v2, v3
	v_cvt_pk_bf16_f32 v117, v4, v5
	ds_read_b128 v[2:5], v120 offset:9248
	s_waitcnt lgkmcnt(3)
	v_mfma_f32_32x32x16_bf16 v[64:79], v[6:9], v[116:119], v[64:79]
	v_cvt_pk_bf16_f32 v132, v15, v224
	v_cvt_pk_bf16_f32 v133, v225, v226
	v_cvt_pk_bf16_f32 v134, v227, v228
	v_cvt_pk_bf16_f32 v135, v229, v230
	v_exp_f32_e32 v0, v96
	v_exp_f32_e32 v15, v97
	s_waitcnt lgkmcnt(2)
	v_mfma_f32_32x32x16_bf16 v[48:63], v[10:13], v[116:119], v[48:63]
	ds_read_b128 v[124:127], v120 offset:9280
	ds_read_b128 v[116:119], v120 offset:9312
	ds_read_b128 v[128:131], v120 offset:13888
	ds_read_b128 v[120:123], v120 offset:13920
	v_cvt_pk_bf16_f32 v136, v231, v232
	v_cvt_pk_bf16_f32 v137, v233, v234
	v_cvt_pk_bf16_f32 v138, v235, v236
	v_cvt_pk_bf16_f32 v139, v237, v238
	s_waitcnt lgkmcnt(4)
	v_mfma_f32_32x32x16_bf16 v[64:79], v[2:5], v[132:135], v[64:79]
	v_exp_f32_e32 v141, v107
	v_cvt_pk_bf16_f32 v224, v239, v240
	v_cvt_pk_bf16_f32 v225, v241, v242
	v_cvt_pk_bf16_f32 v226, v243, v244
	v_cvt_pk_bf16_f32 v227, v245, v246
	v_exp_f32_e32 v143, v109
	v_mfma_f32_32x32x16_bf16 v[48:63], v[112:115], v[132:135], v[48:63]
	v_exp_f32_e32 v132, v98
	v_exp_f32_e32 v133, v99
	v_add_f32_e32 v135, 0, v0
	v_exp_f32_e32 v134, v100
	v_add_f32_e32 v135, v15, v135
	v_add_f32_e32 v135, v132, v135
	v_add_f32_e32 v135, v133, v135
	v_add_f32_e32 v140, v134, v135
	s_waitcnt lgkmcnt(3)
	v_mfma_f32_32x32x16_bf16 v[64:79], v[124:127], v[136:139], v[64:79]
	v_exp_f32_e32 v135, v101
	v_exp_f32_e32 v228, v82
	v_exp_f32_e32 v229, v83
	v_exp_f32_e32 v231, v85
	s_waitcnt lgkmcnt(1)
	v_mfma_f32_32x32x16_bf16 v[48:63], v[128:131], v[136:139], v[48:63]
	v_exp_f32_e32 v136, v102
	v_exp_f32_e32 v137, v103
	v_add_f32_e32 v138, v135, v140
	v_add_f32_e32 v138, v136, v138
	v_add_f32_e32 v142, v137, v138
	v_exp_f32_e32 v138, v104
	v_exp_f32_e32 v139, v105
	v_exp_f32_e32 v140, v106
	v_add_f32_e32 v142, v138, v142
	v_add_f32_e32 v142, v139, v142
	v_mfma_f32_32x32x16_bf16 v[64:79], v[116:119], v[224:227], v[64:79]
	v_add_f32_e32 v142, v140, v142
	v_exp_f32_e32 v232, v86
	v_exp_f32_e32 v233, v87
	v_exp_f32_e32 v235, v89
	s_waitcnt lgkmcnt(0)
	v_mfma_f32_32x32x16_bf16 v[48:63], v[120:123], v[224:227], v[48:63]
	v_add_f32_e32 v226, v141, v142
	v_exp_f32_e32 v142, v108
	v_exp_f32_e32 v224, v110
	v_exp_f32_e32 v225, v111
	v_add_f32_e32 v226, v142, v226
	v_add_f32_e32 v226, v143, v226
	v_add_f32_e32 v226, v224, v226
	v_add_f32_e32 v230, v225, v226
	v_exp_f32_e32 v226, v80
	v_exp_f32_e32 v227, v81
	v_add_f32_e32 v230, v226, v230
	v_exp_f32_e32 v236, v90
	v_add_f32_e32 v230, v227, v230
	v_add_f32_e32 v230, v228, v230
	v_add_f32_e32 v234, v229, v230
	v_exp_f32_e32 v230, v84
	v_exp_f32_e32 v237, v91
	v_add_f32_e32 v234, v230, v234
	v_add_f32_e32 v234, v231, v234
	v_add_f32_e32 v234, v232, v234
	v_add_f32_e32 v238, v233, v234
	v_exp_f32_e32 v234, v88
	v_exp_f32_e32 v239, v93
	v_exp_f32_e32 v240, v94
	v_add_f32_e32 v238, v234, v238
	v_add_f32_e32 v238, v235, v238
	v_add_f32_e32 v238, v236, v238
	v_add_f32_e32 v242, v237, v238
	v_exp_f32_e32 v238, v92
	v_exp_f32_e32 v241, v95
	v_add_f32_e32 v242, v238, v242
	v_add_f32_e32 v242, v239, v242
	v_add_f32_e32 v242, v240, v242
	v_add_f32_e32 v242, v241, v242
	v_cmp_nge_f32_e32 vcc, s24, v242
	s_cbranch_vccz .Lp3f_420
	s_branch .Lp3_rare1
